# attention: the -M slab A operand is a constant register tuple (no K-pad LDS reads or pad init)
# speedup vs baseline: 1.0130x; 1.0130x over previous
; #define STOREKV(buf) do { *(u32x4*)(Kt + (buf) * KT_BYTES + kr0 * KROW + kc0 * 16) = xk0; \
;         if (tid < 256) { *(u32x4*)(Kt + (buf) * KT_BYTES + kr1 * KROW + kc1 * 16) = xa; } \
;         else { tstore_pair(Vt + (buf) * VT_BYTES, VROW, pos64(2 * va), vc8, xa, xb); } } while (0)
; __device__ __forceinline__ void attn_unit2(const bf16_t* Qm, const bf16_t* KVm, const bf16_t* P1, bf16_t* OP, int q0, int h, int klat, int nlat, int kctx, int nt, uchar* lds, bool nostore = false) {
;     ...
;     const int kr0 = tid / 12, kc0 = tid % 12, kr1 = (512 + tid) / 12, kc1 = (512 + tid) % 12;
;     const int tv = tid - 256, va = tv >> 3, vc8 = tv & 7;
;     u32x4 xk0, xa = (u32x4){0u, 0u, 0u, 0u}, xb = xa;
;     ...
;     LOADKV(0); STOREKV(0);
;     __syncthreads();
;     float mA = -1e30f, mB = -1e30f, lA = 0.f, lB = 0.f; f32x16 oA0 = {}, oA1 = {}, oB0 = {}, oB1 = {};
.LBB0_1098:
	s_andn2_saveexec_b64 s[4:5], s[4:5]
	v_add3_u32 v3, 0, v224, v225
	ds_write_b128 v3, v[186:189]
	v_and_b32_e32 v3, 0x7ffffff2, v223
	v_or3_b32 v3, v9, v3, v8
	v_lshlrev_b32_e32 v7, 1, v3
	s_or_b64 exec, exec, s[4:5]
	v_and_b32_e32 v3, 31, v10
	v_mul_u32_u24_e32 v8, 0xd0, v3
	v_add3_u32 v226, 0, v8, v0
	v_and_b32_e32 v8, 64, v210
	v_xor_b32_e32 v0, 32, v210
	v_add_u32_e32 v8, 64, v8
	v_cmp_lt_i32_e32 vcc, v0, v8
	s_lshl_b32 s6, s9, 8
	s_lshl_b32 s74, s13, 1
	v_cndmask_b32_e32 v0, v210, v0, vcc
	s_add_u32 s4, s92, s74
	v_lshlrev_b32_e32 v227, 2, v0
	v_lshlrev_b32_e32 v0, 6, v3
	v_mov_b32_e32 v3, v1
	s_addc_u32 s5, s93, 0
	v_sub_u32_e32 v228, v226, v0
	v_lshl_add_u64 v[196:197], v[2:3], 1, s[30:31]
	v_mov_b32_e32 v3, v11
	v_lshlrev_b32_e32 v0, 3, v5
	v_lshl_add_u64 v[198:199], v[2:3], 1, s[4:5]
	v_cmp_lt_i32_e64 s[42:43], 7, v5
	v_ashrrev_i32_e32 v3, 31, v0
	v_mov_b32_e32 v2, v0
	v_mov_b32_e32 v5, v1
	v_mov_b32_e32 v14, v1
	v_mov_b32_e32 v15, v1
	v_lshl_add_u64 v[200:201], v[0:1], 1, s[30:31]
	v_lshl_add_u64 v[202:203], v[2:3], 1, s[4:5]
	v_add3_u32 v230, 0, v6, v7
	v_lshl_add_u64 v[204:205], s[4:5], 0, v[4:5]
	v_mov_b32_e32 v0, v1
	v_mov_b32_e32 v2, v1
	v_mov_b32_e32 v3, v1
	v_mov_b32_e32 v4, v1
	v_mov_b32_e32 v6, v1
	v_mov_b32_e32 v7, v1
	v_mov_b32_e32 v8, v1
	v_mov_b32_e32 v9, v1
	v_mov_b32_e32 v10, v1
	v_mov_b32_e32 v11, v1
	v_mov_b32_e32 v12, v1
	v_mov_b32_e32 v13, v1
	s_waitcnt lgkmcnt(1)
	v_mov_b64_e32 v[64:65], v[14:15]
	v_mov_b64_e32 v[48:49], v[14:15]
	v_mov_b64_e32 v[32:33], v[14:15]
	v_mov_b64_e32 v[62:63], v[12:13]
	v_mov_b64_e32 v[60:61], v[10:11]
	v_mov_b64_e32 v[58:59], v[8:9]
	v_mov_b64_e32 v[56:57], v[6:7]
	v_mov_b64_e32 v[54:55], v[4:5]
	v_mov_b64_e32 v[52:53], v[2:3]
	v_mov_b64_e32 v[50:51], v[0:1]
	v_mov_b64_e32 v[46:47], v[12:13]
	v_mov_b64_e32 v[44:45], v[10:11]
	v_mov_b64_e32 v[42:43], v[8:9]
	v_mov_b64_e32 v[40:41], v[6:7]
	v_mov_b64_e32 v[38:39], v[4:5]
	v_mov_b64_e32 v[36:37], v[2:3]
	v_mov_b64_e32 v[34:35], v[0:1]
	v_mov_b64_e32 v[30:31], v[12:13]
	v_mov_b64_e32 v[28:29], v[10:11]
	v_mov_b64_e32 v[26:27], v[8:9]
	v_mov_b64_e32 v[24:25], v[6:7]
	v_mov_b64_e32 v[22:23], v[4:5]
	v_mov_b64_e32 v[20:21], v[2:3]
	v_mov_b64_e32 v[18:19], v[0:1]
	v_mov_b64_e32 v[16:17], v[14:15]
	s_mov_b32 s9, 0
	s_add_i32 s13, s6, 0x6040
	s_add_i32 s22, s22, 64
	v_mov_b32_e32 v231, 0
	v_mov_b32_e32 v232, 0
	v_mov_b32_e32 v233, 0
	v_mov_b32_e32 v229, 0
	v_mov_b64_e32 v[14:15], v[12:13]
	v_mov_b64_e32 v[12:13], v[10:11]
	v_mov_b64_e32 v[10:11], v[8:9]
	v_mov_b64_e32 v[8:9], v[6:7]
	v_mov_b64_e32 v[6:7], v[4:5]
	v_mov_b64_e32 v[4:5], v[2:3]
	v_mov_b64_e32 v[2:3], v[0:1]
	v_mov_b32_e32 v197, 0x800
	v_mov_b32_e32 v196, s16
	v_cndmask_b32_e64 v196, v197, v196, s[38:39]
	v_mad_u32_u24 v196, v221, v196, v194
	v_mov_b32_e32 v198, s16
	v_cndmask_b32_e64 v198, v197, v198, s[42:43]
	v_mad_u32_u24 v198, v195, v198, v225
	v_bfe_u32 v199, v206, 5, 3
	v_lshlrev_b32_e32 v199, 4, v199
	v_lshl_add_u32 v199, v223, 11, v199
	v_add_u32_e32 v199, 0x400, v199
	v_cndmask_b32_e64 v197, v198, v199, s[40:41]
	v_mov_b32_e32 v208, 0x3f80
	v_mov_b32_e32 v209, 0
	v_mov_b32_e32 v210, 0
	v_mov_b32_e32 v211, 0
	v_mov_b32_e32 v190, 0
	v_mov_b32_e32 v191, 0
	v_mov_b32_e32 v192, 0
	v_mov_b32_e32 v193, 0
	v_mov_b32_e32 v216, 0
	v_mov_b32_e32 v217, 0
	v_mov_b32_e32 v218, 0
	v_mov_b32_e32 v219, 0
	s_waitcnt lgkmcnt(0)
	s_barrier
	s_branch .LBB0_1103

; #define MFMA32(a, b, c) __builtin_amdgcn_mfma_f32_32x32x16_bf16((a), (b), (c), 0, 0, 0)
; __device__ __forceinline__ void attn_unit2(const bf16_t* Qm, const bf16_t* KVm, const bf16_t* P1, bf16_t* OP, int q0, int h, int klat, int nlat, int kctx, int nt, uchar* lds, bool nostore = false) {
;     ...
;         f32x16 sA0 = {}, sA1 = {}, sB0 = {}, sB1 = {};
;         { const uchar* kb = Kt + buf * KT_BYTES + l32 * KROW + hi * 16;
; #pragma unroll
;           for (int s = 0; s < 6; ++s) { const bf16x8 a0 = *(const bf16x8*)(kb + s * 32), a1 = *(const bf16x8*)(kb + 32 * KROW + s * 32);
;               sA0 = MFMA32(a0, qa[s], sA0); sA1 = MFMA32(a1, qa[s], sA1); sB0 = MFMA32(a0, qb[s], sB0); sB1 = MFMA32(a1, qb[s], sB1); } }
.LBB0_1117:
	s_and_b32 s4, s9, 1
	s_mul_i32 s5, s4, 0x3400
	v_add_u32_e32 v0, s5, v226
	ds_read_b128 v[66:69], v0
	ds_read_b128 v[70:73], v0 offset:32
	ds_read_b128 v[74:77], v0 offset:6656
	ds_read_b128 v[234:237], v0 offset:6688
	v_mfma_f32_32x32x16_bf16 v[114:129], v[208:211], v[216:219], 0
	v_mfma_f32_32x32x16_bf16 v[98:113], v[208:211], v[190:193], 0
	s_waitcnt lgkmcnt(3)
	v_mfma_f32_32x32x16_bf16 v[114:129], v[66:69], v[130:133], v[114:129]
	v_mfma_f32_32x32x16_bf16 v[98:113], v[66:69], v[170:173], v[98:113]
	s_waitcnt lgkmcnt(2)
	v_mfma_f32_32x32x16_bf16 v[114:129], v[70:73], v[134:137], v[114:129]
	v_mfma_f32_32x32x16_bf16 v[98:113], v[70:73], v[138:141], v[98:113]
	ds_read_b128 v[66:69], v0 offset:64
	ds_read_b128 v[70:73], v0 offset:96
	ds_read_b128 v[238:241], v0 offset:6720
	ds_read_b128 v[242:245], v0 offset:6752
	s_waitcnt lgkmcnt(3)
	v_mfma_f32_32x32x16_bf16 v[114:129], v[66:69], v[146:149], v[114:129]
	v_mfma_f32_32x32x16_bf16 v[98:113], v[66:69], v[142:145], v[98:113]
	v_mfma_f32_32x32x16_bf16 v[82:97], v[208:211], v[216:219], 0
	v_mfma_f32_32x32x16_bf16 v[82:97], v[74:77], v[130:133], v[82:97]
	s_waitcnt lgkmcnt(2)
	v_mfma_f32_32x32x16_bf16 v[114:129], v[70:73], v[150:153], v[114:129]
	v_mfma_f32_32x32x16_bf16 v[98:113], v[70:73], v[154:157], v[98:113]
	ds_read_b128 v[66:69], v0 offset:128
	ds_read_b128 v[70:73], v0 offset:160
	ds_read_b128 v[246:249], v0 offset:6784
	ds_read_b128 v[212:215], v0 offset:6816
	v_mfma_f32_32x32x16_bf16 v[82:97], v[234:237], v[134:137], v[82:97]
	s_waitcnt lgkmcnt(3)
	v_mfma_f32_32x32x16_bf16 v[114:129], v[66:69], v[162:165], v[114:129]
	v_mfma_f32_32x32x16_bf16 v[98:113], v[66:69], v[158:161], v[98:113]
	v_mfma_f32_32x32x16_bf16 v[82:97], v[238:241], v[146:149], v[82:97]
	s_waitcnt lgkmcnt(2)
	v_mfma_f32_32x32x16_bf16 v[114:129], v[70:73], v[166:169], v[114:129]
	v_mfma_f32_32x32x16_bf16 v[98:113], v[70:73], v[174:177], v[98:113]
	s_nop 10
	v_max_f32_e32 v0, v115, v115
	v_mfma_f32_32x32x16_bf16 v[66:81], v[74:77], v[170:173], 0
	v_mfma_f32_32x32x16_bf16 v[66:81], v[208:211], v[190:193], v[66:81]
	v_mfma_f32_32x32x16_bf16 v[82:97], v[242:245], v[150:153], v[82:97]
	v_mfma_f32_32x32x16_bf16 v[66:81], v[234:237], v[138:141], v[66:81]
	v_max_f32_e32 v234, v114, v114
	v_max_f32_e32 v0, v234, v0
	s_waitcnt lgkmcnt(1)
	v_mfma_f32_32x32x16_bf16 v[82:97], v[246:249], v[162:165], v[82:97]
	v_mfma_f32_32x32x16_bf16 v[66:81], v[238:241], v[142:145], v[66:81]
	s_waitcnt lgkmcnt(0)
	v_mfma_f32_32x32x16_bf16 v[82:97], v[212:215], v[166:169], v[82:97]
	v_mfma_f32_32x32x16_bf16 v[66:81], v[242:245], v[154:157], v[66:81]
	s_nop 10
	v_max3_f32 v234, v116, v117, v83
	v_max3_f32 v0, v0, v82, v84
	v_max3_f32 v0, v0, v85, v118
	v_max3_f32 v234, v234, v120, v121
	v_max3_f32 v0, v0, v119, v86
	v_max3_f32 v234, v234, v88, v89
	v_max3_f32 v0, v0, v87, v122
	v_mfma_f32_32x32x16_bf16 v[66:81], v[246:249], v[158:161], v[66:81]
	v_mfma_f32_32x32x16_bf16 v[66:81], v[212:215], v[174:177], v[66:81]
	v_max3_f32 v234, v234, v124, v125
	v_max3_f32 v0, v0, v123, v90
	v_max3_f32 v234, v234, v92, v93
	v_max3_f32 v0, v0, v91, v126
	v_max3_f32 v234, v234, v128, v129
	v_max3_f32 v0, v0, v127, v94
	v_max3_f32 v234, v234, v96, v97
	v_max3_f32 v0, v0, v95, v234
	v_max3_f32 v235, v98, v99, v100
	v_max3_f32 v236, v101, v102, v103
	v_max3_f32 v235, v235, v104, v105
	v_max3_f32 v236, v236, v106, v107
	v_max3_f32 v235, v235, v108, v109
	v_max3_f32 v236, v236, v110, v111
	v_max3_f32 v235, v235, v112, v113
	v_max3_f32 v236, v236, v66, v67
	v_max3_f32 v235, v235, v68, v69
	v_max3_f32 v236, v236, v70, v71
	v_max3_f32 v235, v235, v72, v73
	v_max3_f32 v236, v236, v74, v75
	v_max3_f32 v235, v235, v76, v77
	v_max3_f32 v236, v236, v78, v79
	v_max3_f32 v235, v235, v80, v81
	v_max_f32_e32 v235, v235, v236
	v_max_f32_e32 v236, v0, v235
	v_cmp_lt_f32_e32 vcc, 0x41000000, v236
	s_cmp_eq_u32 s9, 0
	s_cbranch_scc1 .Latt_rare
	s_cbranch_vccz .LBB0_1121
